# v14 + steady-state fast iteration in 6 GEMM K-loops: ds_write and global_load interleaved into MFMA stream
# speedup vs baseline: 1.0101x; 1.0045x over previous
; template <bool RES, class Epi>
; DEV void gemm_tile_x(const bf16_t* A0, int lda0, const bf16_t* A1, int lda1, int ksplit,
;                      const bf16_t* Bt, int ldb, int K, char* smem, const float* resb, Epi epi) {
;     ...
;   for (int kt = 0; kt < nk; kt += 2) {
;     GEMM_COMPUTE(sbase);
;     if (kt + 1 < nk) gemm_lds_write(g1, sbase + GST + woff, sbase + GST + GSA + woff);
;     if (kt + 3 < nk) gemm_gload(g1, A0, lda0, A1, lda1, ksplit, Bt, ldb, (kt + 3) * 32, tid);
.LBB0_177:
	s_cmp_lt_i32 s53, 26
	s_cbranch_scc1 .Lfp0_fast
	s_add_i32 s53, s53, 2
	s_cmp_gt_u32 s53, 28
	ds_read_b128 v[196:199], v200
	ds_read_b128 v[208:211], v201 offset:16384
	ds_read_b128 v[224:227], v201 offset:18432
	ds_read_b128 v[228:231], v200 offset:2048
	ds_read_b128 v[252:255], v203 offset:16384
	s_waitcnt lgkmcnt(3)
	v_mfma_f32_32x32x16_bf16 v[112:127], v[196:199], v[208:211], v[112:127]
	s_waitcnt lgkmcnt(2)
	v_mfma_f32_32x32x16_bf16 v[96:111], v[196:199], v[224:227], v[96:111]
	ds_read_b128 v[196:199], v200 offset:4096
	s_waitcnt lgkmcnt(2)
	v_mfma_f32_32x32x16_bf16 v[80:95], v[228:231], v[208:211], v[80:95]
	v_mfma_f32_32x32x16_bf16 v[64:79], v[228:231], v[224:227], v[64:79]
	ds_read_b128 v[228:231], v200 offset:6144
	s_waitcnt lgkmcnt(1)
	v_mfma_f32_32x32x16_bf16 v[48:63], v[196:199], v[208:211], v[48:63]
	v_mfma_f32_32x32x16_bf16 v[32:47], v[196:199], v[224:227], v[32:47]
	ds_read_b128 v[196:199], v202
	s_waitcnt lgkmcnt(1)
	v_mfma_f32_32x32x16_bf16 v[0:15], v[228:231], v[224:227], v[0:15]
	ds_read_b128 v[224:227], v203 offset:18432
	v_mfma_f32_32x32x16_bf16 v[16:31], v[228:231], v[208:211], v[16:31]
	ds_read_b128 v[228:231], v202 offset:2048
	s_waitcnt lgkmcnt(2)
	v_mfma_f32_32x32x16_bf16 v[112:127], v[196:199], v[252:255], v[112:127]
	s_waitcnt lgkmcnt(1)
	v_mfma_f32_32x32x16_bf16 v[96:111], v[196:199], v[224:227], v[96:111]
	ds_read_b128 v[196:199], v202 offset:4096
	s_waitcnt lgkmcnt(1)
	v_mfma_f32_32x32x16_bf16 v[80:95], v[228:231], v[252:255], v[80:95]
	v_mfma_f32_32x32x16_bf16 v[64:79], v[228:231], v[224:227], v[64:79]
	ds_read_b128 v[228:231], v202 offset:6144
	s_waitcnt vmcnt(5)
	ds_write_b128 v179, v[128:131] offset:24576
	s_waitcnt vmcnt(4)
	ds_write_b128 v179, v[136:139] offset:28672
	s_waitcnt vmcnt(3)
	ds_write_b128 v179, v[144:147] offset:32768
	s_waitcnt vmcnt(2)
	ds_write_b128 v179, v[148:151] offset:36864
	s_waitcnt vmcnt(1)
	ds_write_b128 v179, v[160:163] offset:40960
	s_waitcnt vmcnt(0)
	ds_write_b128 v179, v[168:171] offset:45056
	s_waitcnt lgkmcnt(7)
	v_mfma_f32_32x32x16_bf16 v[48:63], v[196:199], v[252:255], v[48:63]
	v_mfma_f32_32x32x16_bf16 v[32:47], v[196:199], v[224:227], v[32:47]
	v_lshl_add_u64 v[198:199], v[192:193], 0, v[190:191]
	v_lshl_add_u64 v[196:197], v[194:195], 0, v[190:191]
	s_waitcnt lgkmcnt(6)
	v_mfma_f32_32x32x16_bf16 v[16:31], v[228:231], v[252:255], v[16:31]
	v_mfma_f32_32x32x16_bf16 v[0:15], v[228:231], v[224:227], v[0:15]
	s_waitcnt lgkmcnt(0)
	s_cbranch_scc1 .LBB0_179
	v_add_co_u32_e32 v128, vcc, 0x1b00000, v198
	s_nop 1
	v_addc_co_u32_e32 v129, vcc, 0, v199, vcc
	v_add_co_u32_e32 v136, vcc, 0x1b20000, v198
	s_nop 1
	v_addc_co_u32_e32 v137, vcc, 0, v199, vcc
	v_add_co_u32_e32 v144, vcc, 0x1b40000, v198
	global_load_dwordx4 v[128:131], v[128:129], off offset:192
	s_nop 0
	global_load_dwordx4 v[136:139], v[136:137], off offset:192
	v_addc_co_u32_e32 v145, vcc, 0, v199, vcc
	v_add_co_u32_e32 v148, vcc, 0x1b60000, v198
	s_nop 1
	v_addc_co_u32_e32 v149, vcc, 0, v199, vcc
	v_add_co_u32_e32 v168, vcc, 0x20000, v196
	global_load_dwordx4 v[144:147], v[144:145], off offset:192
	s_nop 0
	global_load_dwordx4 v[148:151], v[148:149], off offset:192
	v_addc_co_u32_e32 v169, vcc, 0, v197, vcc
	global_load_dwordx4 v[160:163], v[196:197], off offset:192
	s_nop 0
	global_load_dwordx4 v[168:171], v[168:169], off offset:192

; template <bool RES, class Epi>
; DEV void gemm_tile_x(const bf16_t* A0, int lda0, const bf16_t* A1, int lda1, int ksplit,
;                      const bf16_t* Bt, int ldb, int K, char* smem, const float* resb, Epi epi) {
;     ...
;   for (int kt = 0; kt < nk; kt += 2) {
;     GEMM_COMPUTE(sbase);
;     if (kt + 1 < nk) gemm_lds_write(g1, sbase + GST + woff, sbase + GST + GSA + woff);
;     if (kt + 3 < nk) gemm_gload(g1, A0, lda0, A1, lda1, ksplit, Bt, ldb, (kt + 3) * 32, tid);
;     __syncthreads();
;     if (kt + 1 < nk) {
;       GEMM_COMPUTE(sbase + GST);
;       if (kt + 2 < nk) gemm_lds_write(g, sbase + woff, sbase + GSA + woff);
;       if (kt + 4 < nk) gemm_gload(g, A0, lda0, A1, lda1, ksplit, Bt, ldb, (kt + 4) * 32, tid);
;       __syncthreads();
;     }
.Lfp0_fast:
	s_add_i32 s53, s53, 2
	v_lshl_add_u64 v[252:253], v[192:193], 0, v[190:191]
	v_lshl_add_u64 v[254:255], v[194:195], 0, v[190:191]
	s_mov_b32 vcc_hi, 0
	ds_read_b128 v[196:199], v200
	ds_read_b128 v[208:211], v201 offset:16384
	ds_read_b128 v[224:227], v201 offset:18432
	ds_read_b128 v[228:231], v200 offset:2048
	s_waitcnt lgkmcnt(2)
	v_mfma_f32_32x32x16_bf16 v[112:127], v[196:199], v[208:211], v[112:127]
	s_waitcnt lgkmcnt(1)
	v_mfma_f32_32x32x16_bf16 v[96:111], v[196:199], v[224:227], v[96:111]
	ds_read_b128 v[196:199], v200 offset:4096
	s_waitcnt vmcnt(5)
	ds_write_b128 v179, v[128:131] offset:24576
	s_waitcnt vmcnt(4)
	ds_write_b128 v179, v[136:139] offset:28672
	s_waitcnt lgkmcnt(3)
	v_mfma_f32_32x32x16_bf16 v[80:95], v[228:231], v[208:211], v[80:95]
	v_mfma_f32_32x32x16_bf16 v[64:79], v[228:231], v[224:227], v[64:79]
	ds_read_b128 v[228:231], v200 offset:6144
	s_waitcnt vmcnt(3)
	ds_write_b128 v179, v[144:147] offset:32768
	s_waitcnt vmcnt(2)
	ds_write_b128 v179, v[148:151] offset:36864
	s_waitcnt lgkmcnt(5)
	v_mfma_f32_32x32x16_bf16 v[48:63], v[196:199], v[208:211], v[48:63]
	v_mfma_f32_32x32x16_bf16 v[32:47], v[196:199], v[224:227], v[32:47]
	ds_read_b128 v[196:199], v202
	s_waitcnt vmcnt(1)
	ds_write_b128 v179, v[160:163] offset:40960
	s_waitcnt vmcnt(0)
	ds_write_b128 v179, v[168:171] offset:45056
	s_waitcnt lgkmcnt(5)
	v_mfma_f32_32x32x16_bf16 v[16:31], v[228:231], v[208:211], v[16:31]
	ds_read_b128 v[208:211], v203 offset:16384
	v_mfma_f32_32x32x16_bf16 v[0:15], v[228:231], v[224:227], v[0:15]
	ds_read_b128 v[224:227], v203 offset:18432
	ds_read_b128 v[228:231], v202 offset:2048
	s_waitcnt lgkmcnt(2)
	v_mfma_f32_32x32x16_bf16 v[112:127], v[196:199], v[208:211], v[112:127]
	s_waitcnt lgkmcnt(1)
	v_mfma_f32_32x32x16_bf16 v[96:111], v[196:199], v[224:227], v[96:111]
	ds_read_b128 v[196:199], v202 offset:4096
	s_mov_b32 vcc_lo, 0x1b00000
	v_lshl_add_u64 v[128:129], v[252:253], 0, vcc
	global_load_dwordx4 v[128:131], v[128:129], off offset:192
	s_mov_b32 vcc_lo, 0x1b20000
	v_lshl_add_u64 v[136:137], v[252:253], 0, vcc
	global_load_dwordx4 v[136:139], v[136:137], off offset:192
	s_waitcnt lgkmcnt(1)
	v_mfma_f32_32x32x16_bf16 v[80:95], v[228:231], v[208:211], v[80:95]
	v_mfma_f32_32x32x16_bf16 v[64:79], v[228:231], v[224:227], v[64:79]
	ds_read_b128 v[228:231], v202 offset:6144
	s_mov_b32 vcc_lo, 0x1b40000
	v_lshl_add_u64 v[144:145], v[252:253], 0, vcc
	global_load_dwordx4 v[144:147], v[144:145], off offset:192
	s_mov_b32 vcc_lo, 0x1b60000
	v_lshl_add_u64 v[148:149], v[252:253], 0, vcc
	global_load_dwordx4 v[148:151], v[148:149], off offset:192
	s_waitcnt lgkmcnt(1)
	v_mfma_f32_32x32x16_bf16 v[48:63], v[196:199], v[208:211], v[48:63]
	v_mfma_f32_32x32x16_bf16 v[32:47], v[196:199], v[224:227], v[32:47]
	global_load_dwordx4 v[160:163], v[254:255], off offset:192
	s_mov_b32 vcc_lo, 0x20000
	v_lshl_add_u64 v[168:169], v[254:255], 0, vcc
	global_load_dwordx4 v[168:171], v[168:169], off offset:192
	s_waitcnt lgkmcnt(0)
	v_mfma_f32_32x32x16_bf16 v[16:31], v[228:231], v[208:211], v[16:31]
	v_mfma_f32_32x32x16_bf16 v[0:15], v[228:231], v[224:227], v[0:15]
	s_waitcnt lgkmcnt(0)
	s_barrier
	ds_read_b128 v[196:199], v200 offset:24576
	ds_read_b128 v[208:211], v201 offset:40960
	ds_read_b128 v[224:227], v201 offset:43008
	ds_read_b128 v[228:231], v200 offset:26624
	s_waitcnt lgkmcnt(2)
	v_mfma_f32_32x32x16_bf16 v[112:127], v[196:199], v[208:211], v[112:127]
	s_waitcnt lgkmcnt(1)
	v_mfma_f32_32x32x16_bf16 v[96:111], v[196:199], v[224:227], v[96:111]
	ds_read_b128 v[196:199], v200 offset:28672
	ds_write_b128 v179, v[132:135]
	ds_write_b128 v179, v[140:143] offset:4096
	s_waitcnt lgkmcnt(3)
	v_mfma_f32_32x32x16_bf16 v[80:95], v[228:231], v[208:211], v[80:95]
	v_mfma_f32_32x32x16_bf16 v[64:79], v[228:231], v[224:227], v[64:79]
	ds_read_b128 v[228:231], v200 offset:30720
	ds_write_b128 v179, v[152:155] offset:8192
	ds_write_b128 v179, v[156:159] offset:12288
	s_waitcnt lgkmcnt(5)
	v_mfma_f32_32x32x16_bf16 v[48:63], v[196:199], v[208:211], v[48:63]
	v_mfma_f32_32x32x16_bf16 v[32:47], v[196:199], v[224:227], v[32:47]
	ds_read_b128 v[196:199], v202 offset:24576
	ds_write_b128 v179, v[164:167] offset:16384
	ds_write_b128 v179, v[172:175] offset:20480
	s_waitcnt lgkmcnt(5)
	v_mfma_f32_32x32x16_bf16 v[16:31], v[228:231], v[208:211], v[16:31]
	ds_read_b128 v[208:211], v203 offset:40960
	v_mfma_f32_32x32x16_bf16 v[0:15], v[228:231], v[224:227], v[0:15]
	ds_read_b128 v[224:227], v203 offset:43008
	ds_read_b128 v[228:231], v202 offset:26624
	s_waitcnt lgkmcnt(2)
	v_mfma_f32_32x32x16_bf16 v[112:127], v[196:199], v[208:211], v[112:127]
	s_waitcnt lgkmcnt(1)
	v_mfma_f32_32x32x16_bf16 v[96:111], v[196:199], v[224:227], v[96:111]
	ds_read_b128 v[196:199], v202 offset:28672
	s_mov_b32 vcc_lo, 0x1b00000
	v_lshl_add_u64 v[132:133], v[252:253], 0, vcc
	global_load_dwordx4 v[132:135], v[132:133], off offset:256
	s_mov_b32 vcc_lo, 0x1b20000
	v_lshl_add_u64 v[140:141], v[252:253], 0, vcc
	global_load_dwordx4 v[140:143], v[140:141], off offset:256
	s_waitcnt lgkmcnt(1)
	v_mfma_f32_32x32x16_bf16 v[80:95], v[228:231], v[208:211], v[80:95]
	v_mfma_f32_32x32x16_bf16 v[64:79], v[228:231], v[224:227], v[64:79]
	ds_read_b128 v[228:231], v202 offset:30720
	s_mov_b32 vcc_lo, 0x1b40000
	v_lshl_add_u64 v[152:153], v[252:253], 0, vcc
	global_load_dwordx4 v[152:155], v[152:153], off offset:256
	s_mov_b32 vcc_lo, 0x1b60000
	v_lshl_add_u64 v[156:157], v[252:253], 0, vcc
	global_load_dwordx4 v[156:159], v[156:157], off offset:256
	s_waitcnt lgkmcnt(1)
	v_mfma_f32_32x32x16_bf16 v[48:63], v[196:199], v[208:211], v[48:63]
	v_mfma_f32_32x32x16_bf16 v[32:47], v[196:199], v[224:227], v[32:47]
	global_load_dwordx4 v[164:167], v[254:255], off offset:256
	s_mov_b32 vcc_lo, 0x20000
	v_lshl_add_u64 v[172:173], v[254:255], 0, vcc
	global_load_dwordx4 v[172:175], v[172:173], off offset:256
	s_waitcnt lgkmcnt(0)
	v_mfma_f32_32x32x16_bf16 v[16:31], v[228:231], v[208:211], v[16:31]
	v_mfma_f32_32x32x16_bf16 v[0:15], v[228:231], v[224:227], v[0:15]
	v_lshl_add_u64 v[194:195], v[194:195], 0, s[50:51]
	v_lshl_add_u64 v[192:193], v[192:193], 0, s[50:51]
	s_waitcnt lgkmcnt(0)
	s_barrier
	s_branch .LBB0_177

; template <bool RES, class Epi>
; DEV void gemm_tile_x(const bf16_t* A0, int lda0, const bf16_t* A1, int lda1, int ksplit,
;                      const bf16_t* Bt, int ldb, int K, char* smem, const float* resb, Epi epi) {
;     ...
;   for (int kt = 0; kt < nk; kt += 2) {
;     GEMM_COMPUTE(sbase);
;     if (kt + 1 < nk) gemm_lds_write(g1, sbase + GST + woff, sbase + GST + GSA + woff);
;     if (kt + 3 < nk) gemm_gload(g1, A0, lda0, A1, lda1, ksplit, Bt, ldb, (kt + 3) * 32, tid);
.LBB0_260:
	s_cmp_lt_i32 s58, 82
	s_cbranch_scc1 .Lfp1_fast
	s_add_i32 s58, s58, 2
	s_cmpk_gt_u32 s58, 0x54
	ds_read_b128 v[196:199], v200
	ds_read_b128 v[210:213], v201 offset:16384
	ds_read_b128 v[226:229], v201 offset:18432
	ds_read_b128 v[230:233], v200 offset:2048
	ds_read_b128 v[252:255], v203 offset:16384
	s_waitcnt lgkmcnt(3)
	v_mfma_f32_32x32x16_bf16 v[112:127], v[196:199], v[210:213], v[112:127]
	s_waitcnt lgkmcnt(2)
	v_mfma_f32_32x32x16_bf16 v[96:111], v[196:199], v[226:229], v[96:111]
	ds_read_b128 v[196:199], v200 offset:4096
	s_waitcnt lgkmcnt(2)
	v_mfma_f32_32x32x16_bf16 v[80:95], v[230:233], v[210:213], v[80:95]
	v_mfma_f32_32x32x16_bf16 v[64:79], v[230:233], v[226:229], v[64:79]
	ds_read_b128 v[230:233], v200 offset:6144
	s_waitcnt lgkmcnt(1)
	v_mfma_f32_32x32x16_bf16 v[48:63], v[196:199], v[210:213], v[48:63]
	v_mfma_f32_32x32x16_bf16 v[32:47], v[196:199], v[226:229], v[32:47]
	ds_read_b128 v[196:199], v202
	s_waitcnt lgkmcnt(1)
	v_mfma_f32_32x32x16_bf16 v[0:15], v[230:233], v[226:229], v[0:15]
	ds_read_b128 v[226:229], v203 offset:18432
	v_mfma_f32_32x32x16_bf16 v[16:31], v[230:233], v[210:213], v[16:31]
	ds_read_b128 v[230:233], v202 offset:2048
	s_waitcnt lgkmcnt(2)
	v_mfma_f32_32x32x16_bf16 v[112:127], v[196:199], v[252:255], v[112:127]
	s_waitcnt lgkmcnt(1)
	v_mfma_f32_32x32x16_bf16 v[96:111], v[196:199], v[226:229], v[96:111]
	ds_read_b128 v[196:199], v202 offset:4096
	s_waitcnt lgkmcnt(1)
	v_mfma_f32_32x32x16_bf16 v[80:95], v[230:233], v[252:255], v[80:95]
	v_mfma_f32_32x32x16_bf16 v[64:79], v[230:233], v[226:229], v[64:79]
	ds_read_b128 v[230:233], v202 offset:6144
	s_waitcnt vmcnt(5)
	ds_write_b128 v179, v[128:131] offset:24576
	s_waitcnt vmcnt(4)
	ds_write_b128 v179, v[136:139] offset:28672
	s_waitcnt vmcnt(3)
	ds_write_b128 v179, v[144:147] offset:32768
	s_waitcnt vmcnt(2)
	ds_write_b128 v179, v[148:151] offset:36864
	s_waitcnt vmcnt(1)
	ds_write_b128 v179, v[160:163] offset:40960
	s_waitcnt vmcnt(0)
	ds_write_b128 v179, v[168:171] offset:45056
	s_waitcnt lgkmcnt(7)
	v_mfma_f32_32x32x16_bf16 v[48:63], v[196:199], v[252:255], v[48:63]
	v_mfma_f32_32x32x16_bf16 v[32:47], v[196:199], v[226:229], v[32:47]
	v_lshl_add_u64 v[198:199], v[194:195], 0, v[182:183]
	v_lshl_add_u64 v[196:197], v[192:193], 0, v[182:183]
	s_waitcnt lgkmcnt(6)
	v_mfma_f32_32x32x16_bf16 v[16:31], v[230:233], v[252:255], v[16:31]
	v_mfma_f32_32x32x16_bf16 v[0:15], v[230:233], v[226:229], v[0:15]
	s_waitcnt lgkmcnt(0)
	s_cbranch_scc1 .LBB0_262
	v_add_co_u32_e32 v128, vcc, 0x7b00000, v198
	s_nop 1
	v_addc_co_u32_e32 v129, vcc, 0, v199, vcc
	v_add_co_u32_e32 v136, vcc, 0x7b58000, v198
	s_nop 1
	v_addc_co_u32_e32 v137, vcc, 0, v199, vcc
	v_add_co_u32_e32 v144, vcc, 0x7bb0000, v198
	global_load_dwordx4 v[128:131], v[128:129], off offset:192
	s_nop 0
	global_load_dwordx4 v[136:139], v[136:137], off offset:192
	v_addc_co_u32_e32 v145, vcc, 0, v199, vcc
	v_add_co_u32_e32 v148, vcc, 0x7c08000, v198
	s_nop 1
	v_addc_co_u32_e32 v149, vcc, 0, v199, vcc
	v_add_co_u32_e32 v160, vcc, 0xb00000, v196
	global_load_dwordx4 v[144:147], v[144:145], off offset:192
	s_nop 0
	global_load_dwordx4 v[148:151], v[148:149], off offset:192
	v_addc_co_u32_e32 v161, vcc, 0, v197, vcc
	v_add_co_u32_e32 v168, vcc, 0xb58000, v196
	s_nop 1
	v_addc_co_u32_e32 v169, vcc, 0, v197, vcc
	global_load_dwordx4 v[160:163], v[160:161], off offset:192
	s_nop 0
	global_load_dwordx4 v[168:171], v[168:169], off offset:192

; template <bool RES, class Epi>
; DEV void gemm_tile_x(const bf16_t* A0, int lda0, const bf16_t* A1, int lda1, int ksplit,
;                      const bf16_t* Bt, int ldb, int K, char* smem, const float* resb, Epi epi) {
;     ...
;   for (int kt = 0; kt < nk; kt += 2) {
;     GEMM_COMPUTE(sbase);
;     if (kt + 1 < nk) gemm_lds_write(g1, sbase + GST + woff, sbase + GST + GSA + woff);
;     if (kt + 3 < nk) gemm_gload(g1, A0, lda0, A1, lda1, ksplit, Bt, ldb, (kt + 3) * 32, tid);
;     __syncthreads();
;     if (kt + 1 < nk) {
;       GEMM_COMPUTE(sbase + GST);
;       if (kt + 2 < nk) gemm_lds_write(g, sbase + woff, sbase + GSA + woff);
;       if (kt + 4 < nk) gemm_gload(g, A0, lda0, A1, lda1, ksplit, Bt, ldb, (kt + 4) * 32, tid);
;       __syncthreads();
;     }
.Lfp1_fast:
	s_add_i32 s58, s58, 2
	v_lshl_add_u64 v[252:253], v[194:195], 0, v[182:183]
	v_lshl_add_u64 v[254:255], v[192:193], 0, v[182:183]
	s_mov_b32 vcc_hi, 0
	ds_read_b128 v[196:199], v200
	ds_read_b128 v[210:213], v201 offset:16384
	ds_read_b128 v[226:229], v201 offset:18432
	ds_read_b128 v[230:233], v200 offset:2048
	s_waitcnt lgkmcnt(2)
	v_mfma_f32_32x32x16_bf16 v[112:127], v[196:199], v[210:213], v[112:127]
	s_waitcnt lgkmcnt(1)
	v_mfma_f32_32x32x16_bf16 v[96:111], v[196:199], v[226:229], v[96:111]
	ds_read_b128 v[196:199], v200 offset:4096
	s_waitcnt vmcnt(5)
	ds_write_b128 v179, v[128:131] offset:24576
	s_waitcnt vmcnt(4)
	ds_write_b128 v179, v[136:139] offset:28672
	s_waitcnt lgkmcnt(3)
	v_mfma_f32_32x32x16_bf16 v[80:95], v[230:233], v[210:213], v[80:95]
	v_mfma_f32_32x32x16_bf16 v[64:79], v[230:233], v[226:229], v[64:79]
	ds_read_b128 v[230:233], v200 offset:6144
	s_waitcnt vmcnt(3)
	ds_write_b128 v179, v[144:147] offset:32768
	s_waitcnt vmcnt(2)
	ds_write_b128 v179, v[148:151] offset:36864
	s_waitcnt lgkmcnt(5)
	v_mfma_f32_32x32x16_bf16 v[48:63], v[196:199], v[210:213], v[48:63]
	v_mfma_f32_32x32x16_bf16 v[32:47], v[196:199], v[226:229], v[32:47]
	ds_read_b128 v[196:199], v202
	s_waitcnt vmcnt(1)
	ds_write_b128 v179, v[160:163] offset:40960
	s_waitcnt vmcnt(0)
	ds_write_b128 v179, v[168:171] offset:45056
	s_waitcnt lgkmcnt(5)
	v_mfma_f32_32x32x16_bf16 v[16:31], v[230:233], v[210:213], v[16:31]
	ds_read_b128 v[210:213], v203 offset:16384
	v_mfma_f32_32x32x16_bf16 v[0:15], v[230:233], v[226:229], v[0:15]
	ds_read_b128 v[226:229], v203 offset:18432
	ds_read_b128 v[230:233], v202 offset:2048
	s_waitcnt lgkmcnt(2)
	v_mfma_f32_32x32x16_bf16 v[112:127], v[196:199], v[210:213], v[112:127]
	s_waitcnt lgkmcnt(1)
	v_mfma_f32_32x32x16_bf16 v[96:111], v[196:199], v[226:229], v[96:111]
	ds_read_b128 v[196:199], v202 offset:4096
	s_mov_b32 vcc_lo, 0x7b00000
	v_lshl_add_u64 v[128:129], v[252:253], 0, vcc
	global_load_dwordx4 v[128:131], v[128:129], off offset:192
	s_mov_b32 vcc_lo, 0x7b58000
	v_lshl_add_u64 v[136:137], v[252:253], 0, vcc
	global_load_dwordx4 v[136:139], v[136:137], off offset:192
	s_waitcnt lgkmcnt(1)
	v_mfma_f32_32x32x16_bf16 v[80:95], v[230:233], v[210:213], v[80:95]
	v_mfma_f32_32x32x16_bf16 v[64:79], v[230:233], v[226:229], v[64:79]
	ds_read_b128 v[230:233], v202 offset:6144
	s_mov_b32 vcc_lo, 0x7bb0000
	v_lshl_add_u64 v[144:145], v[252:253], 0, vcc
	global_load_dwordx4 v[144:147], v[144:145], off offset:192
	s_mov_b32 vcc_lo, 0x7c08000
	v_lshl_add_u64 v[148:149], v[252:253], 0, vcc
	global_load_dwordx4 v[148:151], v[148:149], off offset:192
	s_waitcnt lgkmcnt(1)
	v_mfma_f32_32x32x16_bf16 v[48:63], v[196:199], v[210:213], v[48:63]
	v_mfma_f32_32x32x16_bf16 v[32:47], v[196:199], v[226:229], v[32:47]
	s_mov_b32 vcc_lo, 0xb00000
	v_lshl_add_u64 v[160:161], v[254:255], 0, vcc
	global_load_dwordx4 v[160:163], v[160:161], off offset:192
	s_mov_b32 vcc_lo, 0xb58000
	v_lshl_add_u64 v[168:169], v[254:255], 0, vcc
	global_load_dwordx4 v[168:171], v[168:169], off offset:192
	s_waitcnt lgkmcnt(0)
	v_mfma_f32_32x32x16_bf16 v[16:31], v[230:233], v[210:213], v[16:31]
	v_mfma_f32_32x32x16_bf16 v[0:15], v[230:233], v[226:229], v[0:15]
	s_waitcnt lgkmcnt(0)
	s_barrier
	ds_read_b128 v[196:199], v200 offset:24576
	ds_read_b128 v[210:213], v201 offset:40960
	ds_read_b128 v[226:229], v201 offset:43008
	ds_read_b128 v[230:233], v200 offset:26624
	s_waitcnt lgkmcnt(2)
	v_mfma_f32_32x32x16_bf16 v[112:127], v[196:199], v[210:213], v[112:127]
	s_waitcnt lgkmcnt(1)
	v_mfma_f32_32x32x16_bf16 v[96:111], v[196:199], v[226:229], v[96:111]
	ds_read_b128 v[196:199], v200 offset:28672
	ds_write_b128 v179, v[132:135]
	ds_write_b128 v179, v[140:143] offset:4096
	s_waitcnt lgkmcnt(3)
	v_mfma_f32_32x32x16_bf16 v[80:95], v[230:233], v[210:213], v[80:95]
	v_mfma_f32_32x32x16_bf16 v[64:79], v[230:233], v[226:229], v[64:79]
	ds_read_b128 v[230:233], v200 offset:30720
	ds_write_b128 v179, v[152:155] offset:8192
	ds_write_b128 v179, v[156:159] offset:12288
	s_waitcnt lgkmcnt(5)
	v_mfma_f32_32x32x16_bf16 v[48:63], v[196:199], v[210:213], v[48:63]
	v_mfma_f32_32x32x16_bf16 v[32:47], v[196:199], v[226:229], v[32:47]
	ds_read_b128 v[196:199], v202 offset:24576
	ds_write_b128 v179, v[164:167] offset:16384
	ds_write_b128 v179, v[172:175] offset:20480
	s_waitcnt lgkmcnt(5)
	v_mfma_f32_32x32x16_bf16 v[16:31], v[230:233], v[210:213], v[16:31]
	ds_read_b128 v[210:213], v203 offset:40960
	v_mfma_f32_32x32x16_bf16 v[0:15], v[230:233], v[226:229], v[0:15]
	ds_read_b128 v[226:229], v203 offset:43008
	ds_read_b128 v[230:233], v202 offset:26624
	s_waitcnt lgkmcnt(2)
	v_mfma_f32_32x32x16_bf16 v[112:127], v[196:199], v[210:213], v[112:127]
	s_waitcnt lgkmcnt(1)
	v_mfma_f32_32x32x16_bf16 v[96:111], v[196:199], v[226:229], v[96:111]
	ds_read_b128 v[196:199], v202 offset:28672
	s_mov_b32 vcc_lo, 0x7b00000
	v_lshl_add_u64 v[132:133], v[252:253], 0, vcc
	global_load_dwordx4 v[132:135], v[132:133], off offset:256
	s_mov_b32 vcc_lo, 0x7b58000
	v_lshl_add_u64 v[140:141], v[252:253], 0, vcc
	global_load_dwordx4 v[140:143], v[140:141], off offset:256
	s_waitcnt lgkmcnt(1)
	v_mfma_f32_32x32x16_bf16 v[80:95], v[230:233], v[210:213], v[80:95]
	v_mfma_f32_32x32x16_bf16 v[64:79], v[230:233], v[226:229], v[64:79]
	ds_read_b128 v[230:233], v202 offset:30720
	s_mov_b32 vcc_lo, 0x7bb0000
	v_lshl_add_u64 v[152:153], v[252:253], 0, vcc
	global_load_dwordx4 v[152:155], v[152:153], off offset:256
	s_mov_b32 vcc_lo, 0x7c08000
	v_lshl_add_u64 v[156:157], v[252:253], 0, vcc
	global_load_dwordx4 v[156:159], v[156:157], off offset:256
	s_waitcnt lgkmcnt(1)
	v_mfma_f32_32x32x16_bf16 v[48:63], v[196:199], v[210:213], v[48:63]
	v_mfma_f32_32x32x16_bf16 v[32:47], v[196:199], v[226:229], v[32:47]
	s_mov_b32 vcc_lo, 0xb00000
	v_lshl_add_u64 v[164:165], v[254:255], 0, vcc
	global_load_dwordx4 v[164:167], v[164:165], off offset:256
	s_mov_b32 vcc_lo, 0xb58000
	v_lshl_add_u64 v[172:173], v[254:255], 0, vcc
	global_load_dwordx4 v[172:175], v[172:173], off offset:256
	s_waitcnt lgkmcnt(0)
	v_mfma_f32_32x32x16_bf16 v[16:31], v[230:233], v[210:213], v[16:31]
	v_mfma_f32_32x32x16_bf16 v[0:15], v[230:233], v[226:229], v[0:15]
	v_lshl_add_u64 v[192:193], v[192:193], 0, s[50:51]
	v_lshl_add_u64 v[194:195], v[194:195], 0, s[50:51]
	s_waitcnt lgkmcnt(0)
	s_barrier
	s_branch .LBB0_260

; template <bool RES, class Epi>
; DEV void gemm_tile_x(const bf16_t* A0, int lda0, const bf16_t* A1, int lda1, int ksplit,
;                      const bf16_t* Bt, int ldb, int K, char* smem, const float* resb, Epi epi) {
;     ...
;   for (int kt = 0; kt < nk; kt += 2) {
;     GEMM_COMPUTE(sbase);
;     if (kt + 1 < nk) gemm_lds_write(g1, sbase + GST + woff, sbase + GST + GSA + woff);
;     if (kt + 3 < nk) gemm_gload(g1, A0, lda0, A1, lda1, ksplit, Bt, ldb, (kt + 3) * 32, tid);
.LBB0_2716:
	s_cmp_lt_i32 s50, 26
	s_cbranch_scc1 .Lfp6_fast
	s_add_i32 s50, s50, 2
	s_cmp_gt_u32 s50, 28
	ds_read_b128 v[210:213], v183
	ds_read_b128 v[232:235], v185 offset:16384
	ds_read_b128 v[236:239], v185 offset:18432
	ds_read_b128 v[240:243], v183 offset:2048
	ds_read_b128 v[252:255], v227 offset:16384
	s_waitcnt lgkmcnt(3)
	v_mfma_f32_32x32x16_bf16 v[112:127], v[210:213], v[232:235], v[112:127]
	s_waitcnt lgkmcnt(2)
	v_mfma_f32_32x32x16_bf16 v[96:111], v[210:213], v[236:239], v[96:111]
	ds_read_b128 v[210:213], v183 offset:4096
	s_waitcnt lgkmcnt(2)
	v_mfma_f32_32x32x16_bf16 v[80:95], v[240:243], v[232:235], v[80:95]
	v_mfma_f32_32x32x16_bf16 v[64:79], v[240:243], v[236:239], v[64:79]
	ds_read_b128 v[240:243], v183 offset:6144
	s_waitcnt lgkmcnt(1)
	v_mfma_f32_32x32x16_bf16 v[48:63], v[210:213], v[232:235], v[48:63]
	v_mfma_f32_32x32x16_bf16 v[32:47], v[210:213], v[236:239], v[32:47]
	ds_read_b128 v[210:213], v187
	s_waitcnt lgkmcnt(1)
	v_mfma_f32_32x32x16_bf16 v[0:15], v[240:243], v[236:239], v[0:15]
	ds_read_b128 v[236:239], v227 offset:18432
	v_mfma_f32_32x32x16_bf16 v[16:31], v[240:243], v[232:235], v[16:31]
	ds_read_b128 v[240:243], v187 offset:2048
	s_waitcnt lgkmcnt(2)
	v_mfma_f32_32x32x16_bf16 v[112:127], v[210:213], v[252:255], v[112:127]
	s_waitcnt lgkmcnt(1)
	v_mfma_f32_32x32x16_bf16 v[96:111], v[210:213], v[236:239], v[96:111]
	ds_read_b128 v[210:213], v187 offset:4096
	s_waitcnt lgkmcnt(1)
	v_mfma_f32_32x32x16_bf16 v[80:95], v[240:243], v[252:255], v[80:95]
	v_mfma_f32_32x32x16_bf16 v[64:79], v[240:243], v[236:239], v[64:79]
	ds_read_b128 v[240:243], v187 offset:6144
	s_waitcnt vmcnt(5)
	ds_write_b128 v179, v[128:131] offset:24576
	s_waitcnt vmcnt(4)
	ds_write_b128 v179, v[136:139] offset:28672
	s_waitcnt vmcnt(3)
	ds_write_b128 v179, v[144:147] offset:32768
	s_waitcnt vmcnt(2)
	ds_write_b128 v179, v[152:155] offset:36864
	s_waitcnt vmcnt(1)
	ds_write_b128 v179, v[160:163] offset:40960
	s_waitcnt vmcnt(0)
	ds_write_b128 v179, v[168:171] offset:45056
	s_waitcnt lgkmcnt(7)
	v_mfma_f32_32x32x16_bf16 v[48:63], v[210:213], v[252:255], v[48:63]
	v_mfma_f32_32x32x16_bf16 v[32:47], v[210:213], v[236:239], v[32:47]
	v_lshl_add_u64 v[212:213], v[208:209], 0, v[200:201]
	v_lshl_add_u64 v[210:211], v[206:207], 0, v[200:201]
	s_waitcnt lgkmcnt(6)
	v_mfma_f32_32x32x16_bf16 v[16:31], v[240:243], v[252:255], v[16:31]
	v_mfma_f32_32x32x16_bf16 v[0:15], v[240:243], v[236:239], v[0:15]
	s_waitcnt lgkmcnt(0)
	s_cbranch_scc1 .LBB0_2718
	v_add_co_u32_e32 v128, vcc, 0xdb00000, v212
	s_nop 1
	v_addc_co_u32_e32 v129, vcc, 0, v213, vcc
	v_add_co_u32_e32 v136, vcc, 0xdb20000, v212
	s_nop 1
	v_addc_co_u32_e32 v137, vcc, 0, v213, vcc
	v_add_co_u32_e32 v144, vcc, 0xdb40000, v212
	global_load_dwordx4 v[128:131], v[128:129], off offset:192
	s_nop 0
	global_load_dwordx4 v[136:139], v[136:137], off offset:192
	v_addc_co_u32_e32 v145, vcc, 0, v213, vcc
	v_add_co_u32_e32 v152, vcc, 0xdb60000, v212
	s_nop 1
	v_addc_co_u32_e32 v153, vcc, 0, v213, vcc
	v_add_co_u32_e32 v160, vcc, 0x400000, v210
	global_load_dwordx4 v[144:147], v[144:145], off offset:192
	s_nop 0
	global_load_dwordx4 v[152:155], v[152:153], off offset:192
	v_addc_co_u32_e32 v161, vcc, 0, v211, vcc
	v_add_co_u32_e32 v168, vcc, 0x420000, v210
	s_nop 1
	v_addc_co_u32_e32 v169, vcc, 0, v211, vcc
	global_load_dwordx4 v[160:163], v[160:161], off offset:192
	s_nop 0
	global_load_dwordx4 v[168:171], v[168:169], off offset:192

; template <bool RES, class Epi>
; DEV void gemm_tile_x(const bf16_t* A0, int lda0, const bf16_t* A1, int lda1, int ksplit,
;                      const bf16_t* Bt, int ldb, int K, char* smem, const float* resb, Epi epi) {
;     ...
;   for (int kt = 0; kt < nk; kt += 2) {
;     GEMM_COMPUTE(sbase);
;     if (kt + 1 < nk) gemm_lds_write(g1, sbase + GST + woff, sbase + GST + GSA + woff);
;     if (kt + 3 < nk) gemm_gload(g1, A0, lda0, A1, lda1, ksplit, Bt, ldb, (kt + 3) * 32, tid);
;     __syncthreads();
;     if (kt + 1 < nk) {
;       GEMM_COMPUTE(sbase + GST);
;       if (kt + 2 < nk) gemm_lds_write(g, sbase + woff, sbase + GSA + woff);
;       if (kt + 4 < nk) gemm_gload(g, A0, lda0, A1, lda1, ksplit, Bt, ldb, (kt + 4) * 32, tid);
;       __syncthreads();
;     }
.Lfp6_fast:
	s_add_i32 s50, s50, 2
	v_lshl_add_u64 v[252:253], v[208:209], 0, v[200:201]
	v_lshl_add_u64 v[254:255], v[206:207], 0, v[200:201]
	s_mov_b32 vcc_hi, 0
	ds_read_b128 v[210:213], v183
	ds_read_b128 v[232:235], v185 offset:16384
	ds_read_b128 v[236:239], v185 offset:18432
	ds_read_b128 v[240:243], v183 offset:2048
	s_waitcnt lgkmcnt(2)
	v_mfma_f32_32x32x16_bf16 v[112:127], v[210:213], v[232:235], v[112:127]
	s_waitcnt lgkmcnt(1)
	v_mfma_f32_32x32x16_bf16 v[96:111], v[210:213], v[236:239], v[96:111]
	ds_read_b128 v[210:213], v183 offset:4096
	s_waitcnt vmcnt(5)
	ds_write_b128 v179, v[128:131] offset:24576
	s_waitcnt vmcnt(4)
	ds_write_b128 v179, v[136:139] offset:28672
	s_waitcnt lgkmcnt(3)
	v_mfma_f32_32x32x16_bf16 v[80:95], v[240:243], v[232:235], v[80:95]
	v_mfma_f32_32x32x16_bf16 v[64:79], v[240:243], v[236:239], v[64:79]
	ds_read_b128 v[240:243], v183 offset:6144
	s_waitcnt vmcnt(3)
	ds_write_b128 v179, v[144:147] offset:32768
	s_waitcnt vmcnt(2)
	ds_write_b128 v179, v[152:155] offset:36864
	s_waitcnt lgkmcnt(5)
	v_mfma_f32_32x32x16_bf16 v[48:63], v[210:213], v[232:235], v[48:63]
	v_mfma_f32_32x32x16_bf16 v[32:47], v[210:213], v[236:239], v[32:47]
	ds_read_b128 v[210:213], v187
	s_waitcnt vmcnt(1)
	ds_write_b128 v179, v[160:163] offset:40960
	s_waitcnt vmcnt(0)
	ds_write_b128 v179, v[168:171] offset:45056
	s_waitcnt lgkmcnt(5)
	v_mfma_f32_32x32x16_bf16 v[16:31], v[240:243], v[232:235], v[16:31]
	ds_read_b128 v[232:235], v227 offset:16384
	v_mfma_f32_32x32x16_bf16 v[0:15], v[240:243], v[236:239], v[0:15]
	ds_read_b128 v[236:239], v227 offset:18432
	ds_read_b128 v[240:243], v187 offset:2048
	s_waitcnt lgkmcnt(2)
	v_mfma_f32_32x32x16_bf16 v[112:127], v[210:213], v[232:235], v[112:127]
	s_waitcnt lgkmcnt(1)
	v_mfma_f32_32x32x16_bf16 v[96:111], v[210:213], v[236:239], v[96:111]
	ds_read_b128 v[210:213], v187 offset:4096
	s_mov_b32 vcc_lo, 0xdb00000
	v_lshl_add_u64 v[128:129], v[252:253], 0, vcc
	global_load_dwordx4 v[128:131], v[128:129], off offset:192
	s_mov_b32 vcc_lo, 0xdb20000
	v_lshl_add_u64 v[136:137], v[252:253], 0, vcc
	global_load_dwordx4 v[136:139], v[136:137], off offset:192
	s_waitcnt lgkmcnt(1)
	v_mfma_f32_32x32x16_bf16 v[80:95], v[240:243], v[232:235], v[80:95]
	v_mfma_f32_32x32x16_bf16 v[64:79], v[240:243], v[236:239], v[64:79]
	ds_read_b128 v[240:243], v187 offset:6144
	s_mov_b32 vcc_lo, 0xdb40000
	v_lshl_add_u64 v[144:145], v[252:253], 0, vcc
	global_load_dwordx4 v[144:147], v[144:145], off offset:192
	s_mov_b32 vcc_lo, 0xdb60000
	v_lshl_add_u64 v[152:153], v[252:253], 0, vcc
	global_load_dwordx4 v[152:155], v[152:153], off offset:192
	s_waitcnt lgkmcnt(1)
	v_mfma_f32_32x32x16_bf16 v[48:63], v[210:213], v[232:235], v[48:63]
	v_mfma_f32_32x32x16_bf16 v[32:47], v[210:213], v[236:239], v[32:47]
	s_mov_b32 vcc_lo, 0x400000
	v_lshl_add_u64 v[160:161], v[254:255], 0, vcc
	global_load_dwordx4 v[160:163], v[160:161], off offset:192
	s_mov_b32 vcc_lo, 0x420000
	v_lshl_add_u64 v[168:169], v[254:255], 0, vcc
	global_load_dwordx4 v[168:171], v[168:169], off offset:192
	s_waitcnt lgkmcnt(0)
	v_mfma_f32_32x32x16_bf16 v[16:31], v[240:243], v[232:235], v[16:31]
	v_mfma_f32_32x32x16_bf16 v[0:15], v[240:243], v[236:239], v[0:15]
	s_waitcnt lgkmcnt(0)
	s_barrier
	ds_read_b128 v[210:213], v183 offset:24576
	ds_read_b128 v[232:235], v185 offset:40960
	ds_read_b128 v[236:239], v185 offset:43008
	ds_read_b128 v[240:243], v183 offset:26624
	s_waitcnt lgkmcnt(2)
	v_mfma_f32_32x32x16_bf16 v[112:127], v[210:213], v[232:235], v[112:127]
	s_waitcnt lgkmcnt(1)
	v_mfma_f32_32x32x16_bf16 v[96:111], v[210:213], v[236:239], v[96:111]
	ds_read_b128 v[210:213], v183 offset:28672
	ds_write_b128 v179, v[132:135]
	ds_write_b128 v179, v[140:143] offset:4096
	s_waitcnt lgkmcnt(3)
	v_mfma_f32_32x32x16_bf16 v[80:95], v[240:243], v[232:235], v[80:95]
	v_mfma_f32_32x32x16_bf16 v[64:79], v[240:243], v[236:239], v[64:79]
	ds_read_b128 v[240:243], v183 offset:30720
	ds_write_b128 v179, v[148:151] offset:8192
	ds_write_b128 v179, v[156:159] offset:12288
	s_waitcnt lgkmcnt(5)
	v_mfma_f32_32x32x16_bf16 v[48:63], v[210:213], v[232:235], v[48:63]
	v_mfma_f32_32x32x16_bf16 v[32:47], v[210:213], v[236:239], v[32:47]
	ds_read_b128 v[210:213], v187 offset:24576
	ds_write_b128 v179, v[164:167] offset:16384
	ds_write_b128 v179, v[172:175] offset:20480
	s_waitcnt lgkmcnt(5)
	v_mfma_f32_32x32x16_bf16 v[16:31], v[240:243], v[232:235], v[16:31]
	ds_read_b128 v[232:235], v227 offset:40960
	v_mfma_f32_32x32x16_bf16 v[0:15], v[240:243], v[236:239], v[0:15]
	ds_read_b128 v[236:239], v227 offset:43008
	ds_read_b128 v[240:243], v187 offset:26624
	s_waitcnt lgkmcnt(2)
	v_mfma_f32_32x32x16_bf16 v[112:127], v[210:213], v[232:235], v[112:127]
	s_waitcnt lgkmcnt(1)
	v_mfma_f32_32x32x16_bf16 v[96:111], v[210:213], v[236:239], v[96:111]
	ds_read_b128 v[210:213], v187 offset:28672
	s_mov_b32 vcc_lo, 0xdb00000
	v_lshl_add_u64 v[132:133], v[252:253], 0, vcc
	global_load_dwordx4 v[132:135], v[132:133], off offset:256
	s_mov_b32 vcc_lo, 0xdb20000
	v_lshl_add_u64 v[140:141], v[252:253], 0, vcc
	global_load_dwordx4 v[140:143], v[140:141], off offset:256
	s_waitcnt lgkmcnt(1)
	v_mfma_f32_32x32x16_bf16 v[80:95], v[240:243], v[232:235], v[80:95]
	v_mfma_f32_32x32x16_bf16 v[64:79], v[240:243], v[236:239], v[64:79]
	ds_read_b128 v[240:243], v187 offset:30720
	s_mov_b32 vcc_lo, 0xdb40000
	v_lshl_add_u64 v[148:149], v[252:253], 0, vcc
	global_load_dwordx4 v[148:151], v[148:149], off offset:256
	s_mov_b32 vcc_lo, 0xdb60000
	v_lshl_add_u64 v[156:157], v[252:253], 0, vcc
	global_load_dwordx4 v[156:159], v[156:157], off offset:256
	s_waitcnt lgkmcnt(1)
	v_mfma_f32_32x32x16_bf16 v[48:63], v[210:213], v[232:235], v[48:63]
	v_mfma_f32_32x32x16_bf16 v[32:47], v[210:213], v[236:239], v[32:47]
	s_mov_b32 vcc_lo, 0x400000
	v_lshl_add_u64 v[164:165], v[254:255], 0, vcc
	global_load_dwordx4 v[164:167], v[164:165], off offset:256
	s_mov_b32 vcc_lo, 0x420000
	v_lshl_add_u64 v[172:173], v[254:255], 0, vcc
	global_load_dwordx4 v[172:175], v[172:173], off offset:256
	s_waitcnt lgkmcnt(0)
	v_mfma_f32_32x32x16_bf16 v[16:31], v[240:243], v[232:235], v[16:31]
	v_mfma_f32_32x32x16_bf16 v[0:15], v[240:243], v[236:239], v[0:15]
	v_lshl_add_u64 v[206:207], v[206:207], 0, s[52:53]
	v_lshl_add_u64 v[208:209], v[208:209], 0, s[52:53]
	s_waitcnt lgkmcnt(0)
	s_barrier
	s_branch .LBB0_2716

; template <bool RES, class Epi>
; DEV void gemm_tile_x(const bf16_t* A0, int lda0, const bf16_t* A1, int lda1, int ksplit,
;                      const bf16_t* Bt, int ldb, int K, char* smem, const float* resb, Epi epi) {
;     ...
;   for (int kt = 0; kt < nk; kt += 2) {
;     GEMM_COMPUTE(sbase);
;     if (kt + 1 < nk) gemm_lds_write(g1, sbase + GST + woff, sbase + GST + GSA + woff);
;     if (kt + 3 < nk) gemm_gload(g1, A0, lda0, A1, lda1, ksplit, Bt, ldb, (kt + 3) * 32, tid);
.LBB0_2726:
	s_cmp_lt_i32 s50, 26
	s_cbranch_scc1 .Lfp7_fast
	s_add_i32 s50, s50, 2
	s_cmp_gt_u32 s50, 28
	ds_read_b128 v[208:211], v183
	ds_read_b128 v[232:235], v185 offset:16384
	ds_read_b128 v[236:239], v185 offset:18432
	ds_read_b128 v[240:243], v183 offset:2048
	ds_read_b128 v[252:255], v227 offset:16384
	s_waitcnt lgkmcnt(3)
	v_mfma_f32_32x32x16_bf16 v[112:127], v[208:211], v[232:235], v[112:127]
	s_waitcnt lgkmcnt(2)
	v_mfma_f32_32x32x16_bf16 v[96:111], v[208:211], v[236:239], v[96:111]
	ds_read_b128 v[208:211], v183 offset:4096
	s_waitcnt lgkmcnt(2)
	v_mfma_f32_32x32x16_bf16 v[80:95], v[240:243], v[232:235], v[80:95]
	v_mfma_f32_32x32x16_bf16 v[64:79], v[240:243], v[236:239], v[64:79]
	ds_read_b128 v[240:243], v183 offset:6144
	s_waitcnt lgkmcnt(1)
	v_mfma_f32_32x32x16_bf16 v[48:63], v[208:211], v[232:235], v[48:63]
	v_mfma_f32_32x32x16_bf16 v[32:47], v[208:211], v[236:239], v[32:47]
	ds_read_b128 v[208:211], v187
	s_waitcnt lgkmcnt(1)
	v_mfma_f32_32x32x16_bf16 v[0:15], v[240:243], v[236:239], v[0:15]
	ds_read_b128 v[236:239], v227 offset:18432
	v_mfma_f32_32x32x16_bf16 v[16:31], v[240:243], v[232:235], v[16:31]
	ds_read_b128 v[240:243], v187 offset:2048
	s_waitcnt lgkmcnt(2)
	v_mfma_f32_32x32x16_bf16 v[112:127], v[208:211], v[252:255], v[112:127]
	s_waitcnt lgkmcnt(1)
	v_mfma_f32_32x32x16_bf16 v[96:111], v[208:211], v[236:239], v[96:111]
	ds_read_b128 v[208:211], v187 offset:4096
	s_waitcnt lgkmcnt(1)
	v_mfma_f32_32x32x16_bf16 v[80:95], v[240:243], v[252:255], v[80:95]
	v_mfma_f32_32x32x16_bf16 v[64:79], v[240:243], v[236:239], v[64:79]
	ds_read_b128 v[240:243], v187 offset:6144
	s_waitcnt vmcnt(5)
	ds_write_b128 v179, v[128:131] offset:24576
	s_waitcnt vmcnt(4)
	ds_write_b128 v179, v[136:139] offset:28672
	s_waitcnt vmcnt(3)
	ds_write_b128 v179, v[144:147] offset:32768
	s_waitcnt vmcnt(2)
	ds_write_b128 v179, v[152:155] offset:36864
	s_waitcnt vmcnt(1)
	ds_write_b128 v179, v[160:163] offset:40960
	s_waitcnt vmcnt(0)
	ds_write_b128 v179, v[168:171] offset:45056
	s_waitcnt lgkmcnt(7)
	v_mfma_f32_32x32x16_bf16 v[48:63], v[208:211], v[252:255], v[48:63]
	v_mfma_f32_32x32x16_bf16 v[32:47], v[208:211], v[236:239], v[32:47]
	v_lshl_add_u64 v[210:211], v[206:207], 0, v[200:201]
	v_lshl_add_u64 v[208:209], v[204:205], 0, v[200:201]
	s_waitcnt lgkmcnt(6)
	v_mfma_f32_32x32x16_bf16 v[16:31], v[240:243], v[252:255], v[16:31]
	v_mfma_f32_32x32x16_bf16 v[0:15], v[240:243], v[236:239], v[0:15]
	s_waitcnt lgkmcnt(0)
	s_cbranch_scc1 .LBB0_2728
	v_add_co_u32_e32 v128, vcc, 0xdb00000, v210
	s_nop 1
	v_addc_co_u32_e32 v129, vcc, 0, v211, vcc
	v_add_co_u32_e32 v136, vcc, 0xdb20000, v210
	s_nop 1
	v_addc_co_u32_e32 v137, vcc, 0, v211, vcc
	v_add_co_u32_e32 v144, vcc, 0xdb40000, v210
	global_load_dwordx4 v[128:131], v[128:129], off offset:192
	s_nop 0
	global_load_dwordx4 v[136:139], v[136:137], off offset:192
	v_addc_co_u32_e32 v145, vcc, 0, v211, vcc
	v_add_co_u32_e32 v152, vcc, 0xdb60000, v210
	s_nop 1
	v_addc_co_u32_e32 v153, vcc, 0, v211, vcc
	v_add_co_u32_e32 v160, vcc, 0x400000, v208
	global_load_dwordx4 v[144:147], v[144:145], off offset:192
	s_nop 0
	global_load_dwordx4 v[152:155], v[152:153], off offset:192
	v_addc_co_u32_e32 v161, vcc, 0, v209, vcc
	v_add_co_u32_e32 v168, vcc, 0x420000, v208
	s_nop 1
	v_addc_co_u32_e32 v169, vcc, 0, v209, vcc
	global_load_dwordx4 v[160:163], v[160:161], off offset:192
	s_nop 0
	global_load_dwordx4 v[168:171], v[168:169], off offset:192

; template <bool RES, class Epi>
; DEV void gemm_tile_x(const bf16_t* A0, int lda0, const bf16_t* A1, int lda1, int ksplit,
;                      const bf16_t* Bt, int ldb, int K, char* smem, const float* resb, Epi epi) {
;     ...
;   for (int kt = 0; kt < nk; kt += 2) {
;     GEMM_COMPUTE(sbase);
;     if (kt + 1 < nk) gemm_lds_write(g1, sbase + GST + woff, sbase + GST + GSA + woff);
;     if (kt + 3 < nk) gemm_gload(g1, A0, lda0, A1, lda1, ksplit, Bt, ldb, (kt + 3) * 32, tid);
;     __syncthreads();
;     if (kt + 1 < nk) {
;       GEMM_COMPUTE(sbase + GST);
;       if (kt + 2 < nk) gemm_lds_write(g, sbase + woff, sbase + GSA + woff);
;       if (kt + 4 < nk) gemm_gload(g, A0, lda0, A1, lda1, ksplit, Bt, ldb, (kt + 4) * 32, tid);
;       __syncthreads();
;     }
.Lfp7_fast:
	s_add_i32 s50, s50, 2
	v_lshl_add_u64 v[252:253], v[206:207], 0, v[200:201]
	v_lshl_add_u64 v[254:255], v[204:205], 0, v[200:201]
	s_mov_b32 vcc_hi, 0
	ds_read_b128 v[208:211], v183
	ds_read_b128 v[232:235], v185 offset:16384
	ds_read_b128 v[236:239], v185 offset:18432
	ds_read_b128 v[240:243], v183 offset:2048
	s_waitcnt lgkmcnt(2)
	v_mfma_f32_32x32x16_bf16 v[112:127], v[208:211], v[232:235], v[112:127]
	s_waitcnt lgkmcnt(1)
	v_mfma_f32_32x32x16_bf16 v[96:111], v[208:211], v[236:239], v[96:111]
	ds_read_b128 v[208:211], v183 offset:4096
	s_waitcnt vmcnt(5)
	ds_write_b128 v179, v[128:131] offset:24576
	s_waitcnt vmcnt(4)
	ds_write_b128 v179, v[136:139] offset:28672
	s_waitcnt lgkmcnt(3)
	v_mfma_f32_32x32x16_bf16 v[80:95], v[240:243], v[232:235], v[80:95]
	v_mfma_f32_32x32x16_bf16 v[64:79], v[240:243], v[236:239], v[64:79]
	ds_read_b128 v[240:243], v183 offset:6144
	s_waitcnt vmcnt(3)
	ds_write_b128 v179, v[144:147] offset:32768
	s_waitcnt vmcnt(2)
	ds_write_b128 v179, v[152:155] offset:36864
	s_waitcnt lgkmcnt(5)
	v_mfma_f32_32x32x16_bf16 v[48:63], v[208:211], v[232:235], v[48:63]
	v_mfma_f32_32x32x16_bf16 v[32:47], v[208:211], v[236:239], v[32:47]
	ds_read_b128 v[208:211], v187
	s_waitcnt vmcnt(1)
	ds_write_b128 v179, v[160:163] offset:40960
	s_waitcnt vmcnt(0)
	ds_write_b128 v179, v[168:171] offset:45056
	s_waitcnt lgkmcnt(5)
	v_mfma_f32_32x32x16_bf16 v[16:31], v[240:243], v[232:235], v[16:31]
	ds_read_b128 v[232:235], v227 offset:16384
	v_mfma_f32_32x32x16_bf16 v[0:15], v[240:243], v[236:239], v[0:15]
	ds_read_b128 v[236:239], v227 offset:18432
	ds_read_b128 v[240:243], v187 offset:2048
	s_waitcnt lgkmcnt(2)
	v_mfma_f32_32x32x16_bf16 v[112:127], v[208:211], v[232:235], v[112:127]
	s_waitcnt lgkmcnt(1)
	v_mfma_f32_32x32x16_bf16 v[96:111], v[208:211], v[236:239], v[96:111]
	ds_read_b128 v[208:211], v187 offset:4096
	s_mov_b32 vcc_lo, 0xdb00000
	v_lshl_add_u64 v[128:129], v[252:253], 0, vcc
	global_load_dwordx4 v[128:131], v[128:129], off offset:192
	s_mov_b32 vcc_lo, 0xdb20000
	v_lshl_add_u64 v[136:137], v[252:253], 0, vcc
	global_load_dwordx4 v[136:139], v[136:137], off offset:192
	s_waitcnt lgkmcnt(1)
	v_mfma_f32_32x32x16_bf16 v[80:95], v[240:243], v[232:235], v[80:95]
	v_mfma_f32_32x32x16_bf16 v[64:79], v[240:243], v[236:239], v[64:79]
	ds_read_b128 v[240:243], v187 offset:6144
	s_mov_b32 vcc_lo, 0xdb40000
	v_lshl_add_u64 v[144:145], v[252:253], 0, vcc
	global_load_dwordx4 v[144:147], v[144:145], off offset:192
	s_mov_b32 vcc_lo, 0xdb60000
	v_lshl_add_u64 v[152:153], v[252:253], 0, vcc
	global_load_dwordx4 v[152:155], v[152:153], off offset:192
	s_waitcnt lgkmcnt(1)
	v_mfma_f32_32x32x16_bf16 v[48:63], v[208:211], v[232:235], v[48:63]
	v_mfma_f32_32x32x16_bf16 v[32:47], v[208:211], v[236:239], v[32:47]
	s_mov_b32 vcc_lo, 0x400000
	v_lshl_add_u64 v[160:161], v[254:255], 0, vcc
	global_load_dwordx4 v[160:163], v[160:161], off offset:192
	s_mov_b32 vcc_lo, 0x420000
	v_lshl_add_u64 v[168:169], v[254:255], 0, vcc
	global_load_dwordx4 v[168:171], v[168:169], off offset:192
	s_waitcnt lgkmcnt(0)
	v_mfma_f32_32x32x16_bf16 v[16:31], v[240:243], v[232:235], v[16:31]
	v_mfma_f32_32x32x16_bf16 v[0:15], v[240:243], v[236:239], v[0:15]
	s_waitcnt lgkmcnt(0)
	s_barrier
	ds_read_b128 v[208:211], v183 offset:24576
	ds_read_b128 v[232:235], v185 offset:40960
	ds_read_b128 v[236:239], v185 offset:43008
	ds_read_b128 v[240:243], v183 offset:26624
	s_waitcnt lgkmcnt(2)
	v_mfma_f32_32x32x16_bf16 v[112:127], v[208:211], v[232:235], v[112:127]
	s_waitcnt lgkmcnt(1)
	v_mfma_f32_32x32x16_bf16 v[96:111], v[208:211], v[236:239], v[96:111]
	ds_read_b128 v[208:211], v183 offset:28672
	ds_write_b128 v179, v[132:135]
	ds_write_b128 v179, v[140:143] offset:4096
	s_waitcnt lgkmcnt(3)
	v_mfma_f32_32x32x16_bf16 v[80:95], v[240:243], v[232:235], v[80:95]
	v_mfma_f32_32x32x16_bf16 v[64:79], v[240:243], v[236:239], v[64:79]
	ds_read_b128 v[240:243], v183 offset:30720
	ds_write_b128 v179, v[148:151] offset:8192
	ds_write_b128 v179, v[156:159] offset:12288
	s_waitcnt lgkmcnt(5)
	v_mfma_f32_32x32x16_bf16 v[48:63], v[208:211], v[232:235], v[48:63]
	v_mfma_f32_32x32x16_bf16 v[32:47], v[208:211], v[236:239], v[32:47]
	ds_read_b128 v[208:211], v187 offset:24576
	ds_write_b128 v179, v[164:167] offset:16384
	ds_write_b128 v179, v[172:175] offset:20480
	s_waitcnt lgkmcnt(5)
	v_mfma_f32_32x32x16_bf16 v[16:31], v[240:243], v[232:235], v[16:31]
	ds_read_b128 v[232:235], v227 offset:40960
	v_mfma_f32_32x32x16_bf16 v[0:15], v[240:243], v[236:239], v[0:15]
	ds_read_b128 v[236:239], v227 offset:43008
	ds_read_b128 v[240:243], v187 offset:26624
	s_waitcnt lgkmcnt(2)
	v_mfma_f32_32x32x16_bf16 v[112:127], v[208:211], v[232:235], v[112:127]
	s_waitcnt lgkmcnt(1)
	v_mfma_f32_32x32x16_bf16 v[96:111], v[208:211], v[236:239], v[96:111]
	ds_read_b128 v[208:211], v187 offset:28672
	s_mov_b32 vcc_lo, 0xdb00000
	v_lshl_add_u64 v[132:133], v[252:253], 0, vcc
	global_load_dwordx4 v[132:135], v[132:133], off offset:256
	s_mov_b32 vcc_lo, 0xdb20000
	v_lshl_add_u64 v[140:141], v[252:253], 0, vcc
	global_load_dwordx4 v[140:143], v[140:141], off offset:256
	s_waitcnt lgkmcnt(1)
	v_mfma_f32_32x32x16_bf16 v[80:95], v[240:243], v[232:235], v[80:95]
	v_mfma_f32_32x32x16_bf16 v[64:79], v[240:243], v[236:239], v[64:79]
	ds_read_b128 v[240:243], v187 offset:30720
	s_mov_b32 vcc_lo, 0xdb40000
	v_lshl_add_u64 v[148:149], v[252:253], 0, vcc
	global_load_dwordx4 v[148:151], v[148:149], off offset:256
	s_mov_b32 vcc_lo, 0xdb60000
	v_lshl_add_u64 v[156:157], v[252:253], 0, vcc
	global_load_dwordx4 v[156:159], v[156:157], off offset:256
	s_waitcnt lgkmcnt(1)
	v_mfma_f32_32x32x16_bf16 v[48:63], v[208:211], v[232:235], v[48:63]
	v_mfma_f32_32x32x16_bf16 v[32:47], v[208:211], v[236:239], v[32:47]
	s_mov_b32 vcc_lo, 0x400000
	v_lshl_add_u64 v[164:165], v[254:255], 0, vcc
	global_load_dwordx4 v[164:167], v[164:165], off offset:256
	s_mov_b32 vcc_lo, 0x420000
	v_lshl_add_u64 v[172:173], v[254:255], 0, vcc
	global_load_dwordx4 v[172:175], v[172:173], off offset:256
	s_waitcnt lgkmcnt(0)
	v_mfma_f32_32x32x16_bf16 v[16:31], v[240:243], v[232:235], v[16:31]
	v_mfma_f32_32x32x16_bf16 v[0:15], v[240:243], v[236:239], v[0:15]
	v_lshl_add_u64 v[204:205], v[204:205], 0, s[52:53]
	v_lshl_add_u64 v[206:207], v[206:207], 0, s[52:53]
	s_waitcnt lgkmcnt(0)
	s_barrier
	s_branch .LBB0_2726

; template <bool RES, class Epi>
; DEV void gemm_tile_x(const bf16_t* A0, int lda0, const bf16_t* A1, int lda1, int ksplit,
;                      const bf16_t* Bt, int ldb, int K, char* smem, const float* resb, Epi epi) {
;     ...
;   for (int kt = 0; kt < nk; kt += 2) {
;     GEMM_COMPUTE(sbase);
;     if (kt + 1 < nk) gemm_lds_write(g1, sbase + GST + woff, sbase + GST + GSA + woff);
;     if (kt + 3 < nk) gemm_gload(g1, A0, lda0, A1, lda1, ksplit, Bt, ldb, (kt + 3) * 32, tid);
.LBB0_3203:
	s_cmp_lt_i32 s53, 26
	s_cbranch_scc1 .Lfp9_fast
	s_add_i32 s53, s53, 2
	s_cmp_gt_u32 s53, 28
	ds_read_b128 v[196:199], v200
	ds_read_b128 v[208:211], v201 offset:16384
	ds_read_b128 v[228:231], v201 offset:18432
	ds_read_b128 v[232:235], v200 offset:2048
	ds_read_b128 v[252:255], v203 offset:16384
	s_waitcnt lgkmcnt(3)
	v_mfma_f32_32x32x16_bf16 v[112:127], v[196:199], v[208:211], v[112:127]
	s_waitcnt lgkmcnt(2)
	v_mfma_f32_32x32x16_bf16 v[96:111], v[196:199], v[228:231], v[96:111]
	ds_read_b128 v[196:199], v200 offset:4096
	s_waitcnt lgkmcnt(2)
	v_mfma_f32_32x32x16_bf16 v[80:95], v[232:235], v[208:211], v[80:95]
	v_mfma_f32_32x32x16_bf16 v[64:79], v[232:235], v[228:231], v[64:79]
	ds_read_b128 v[232:235], v200 offset:6144
	s_waitcnt lgkmcnt(1)
	v_mfma_f32_32x32x16_bf16 v[48:63], v[196:199], v[208:211], v[48:63]
	v_mfma_f32_32x32x16_bf16 v[32:47], v[196:199], v[228:231], v[32:47]
	ds_read_b128 v[196:199], v202
	s_waitcnt lgkmcnt(1)
	v_mfma_f32_32x32x16_bf16 v[0:15], v[232:235], v[228:231], v[0:15]
	ds_read_b128 v[228:231], v203 offset:18432
	v_mfma_f32_32x32x16_bf16 v[16:31], v[232:235], v[208:211], v[16:31]
	ds_read_b128 v[232:235], v202 offset:2048
	s_waitcnt lgkmcnt(2)
	v_mfma_f32_32x32x16_bf16 v[112:127], v[196:199], v[252:255], v[112:127]
	s_waitcnt lgkmcnt(1)
	v_mfma_f32_32x32x16_bf16 v[96:111], v[196:199], v[228:231], v[96:111]
	ds_read_b128 v[196:199], v202 offset:4096
	s_waitcnt lgkmcnt(1)
	v_mfma_f32_32x32x16_bf16 v[80:95], v[232:235], v[252:255], v[80:95]
	v_mfma_f32_32x32x16_bf16 v[64:79], v[232:235], v[228:231], v[64:79]
	ds_read_b128 v[232:235], v202 offset:6144
	s_waitcnt vmcnt(5)
	ds_write_b128 v179, v[128:131] offset:24576
	s_waitcnt vmcnt(4)
	ds_write_b128 v179, v[136:139] offset:28672
	s_waitcnt vmcnt(3)
	ds_write_b128 v179, v[144:147] offset:32768
	s_waitcnt vmcnt(2)
	ds_write_b128 v179, v[148:151] offset:36864
	s_waitcnt vmcnt(1)
	ds_write_b128 v179, v[160:163] offset:40960
	s_waitcnt vmcnt(0)
	ds_write_b128 v179, v[168:171] offset:45056
	s_waitcnt lgkmcnt(7)
	v_mfma_f32_32x32x16_bf16 v[48:63], v[196:199], v[252:255], v[48:63]
	v_mfma_f32_32x32x16_bf16 v[32:47], v[196:199], v[228:231], v[32:47]
	v_lshl_add_u64 v[198:199], v[192:193], 0, v[190:191]
	v_lshl_add_u64 v[196:197], v[194:195], 0, v[190:191]
	s_waitcnt lgkmcnt(6)
	v_mfma_f32_32x32x16_bf16 v[16:31], v[232:235], v[252:255], v[16:31]
	v_mfma_f32_32x32x16_bf16 v[0:15], v[232:235], v[228:231], v[0:15]
	s_waitcnt lgkmcnt(0)
	s_cbranch_scc1 .LBB0_3205
	v_add_co_u32_e32 v128, vcc, 0x1b00000, v198
	s_nop 1
	v_addc_co_u32_e32 v129, vcc, 0, v199, vcc
	v_add_co_u32_e32 v136, vcc, 0x1b20000, v198
	s_nop 1
	v_addc_co_u32_e32 v137, vcc, 0, v199, vcc
	v_add_co_u32_e32 v144, vcc, 0x1b40000, v198
	global_load_dwordx4 v[128:131], v[128:129], off offset:192
	s_nop 0
	global_load_dwordx4 v[136:139], v[136:137], off offset:192
	v_addc_co_u32_e32 v145, vcc, 0, v199, vcc
	v_add_co_u32_e32 v148, vcc, 0x1b60000, v198
	s_nop 1
	v_addc_co_u32_e32 v149, vcc, 0, v199, vcc
	v_add_co_u32_e32 v160, vcc, 0xa00000, v196
	global_load_dwordx4 v[144:147], v[144:145], off offset:192
	s_nop 0
	global_load_dwordx4 v[148:151], v[148:149], off offset:192
	v_addc_co_u32_e32 v161, vcc, 0, v197, vcc
	v_add_co_u32_e32 v168, vcc, 0xa20000, v196
	s_nop 1
	v_addc_co_u32_e32 v169, vcc, 0, v197, vcc
	global_load_dwordx4 v[160:163], v[160:161], off offset:192
	s_nop 0
	global_load_dwordx4 v[168:171], v[168:169], off offset:192

; template <bool RES, class Epi>
; DEV void gemm_tile_x(const bf16_t* A0, int lda0, const bf16_t* A1, int lda1, int ksplit,
;                      const bf16_t* Bt, int ldb, int K, char* smem, const float* resb, Epi epi) {
;     ...
;   for (int kt = 0; kt < nk; kt += 2) {
;     GEMM_COMPUTE(sbase);
;     if (kt + 1 < nk) gemm_lds_write(g1, sbase + GST + woff, sbase + GST + GSA + woff);
;     if (kt + 3 < nk) gemm_gload(g1, A0, lda0, A1, lda1, ksplit, Bt, ldb, (kt + 3) * 32, tid);
;     __syncthreads();
;     if (kt + 1 < nk) {
;       GEMM_COMPUTE(sbase + GST);
;       if (kt + 2 < nk) gemm_lds_write(g, sbase + woff, sbase + GSA + woff);
;       if (kt + 4 < nk) gemm_gload(g, A0, lda0, A1, lda1, ksplit, Bt, ldb, (kt + 4) * 32, tid);
;       __syncthreads();
;     }
.Lfp9_fast:
	s_add_i32 s53, s53, 2
	v_lshl_add_u64 v[252:253], v[192:193], 0, v[190:191]
	v_lshl_add_u64 v[254:255], v[194:195], 0, v[190:191]
	s_mov_b32 vcc_hi, 0
	ds_read_b128 v[196:199], v200
	ds_read_b128 v[208:211], v201 offset:16384
	ds_read_b128 v[228:231], v201 offset:18432
	ds_read_b128 v[232:235], v200 offset:2048
	s_waitcnt lgkmcnt(2)
	v_mfma_f32_32x32x16_bf16 v[112:127], v[196:199], v[208:211], v[112:127]
	s_waitcnt lgkmcnt(1)
	v_mfma_f32_32x32x16_bf16 v[96:111], v[196:199], v[228:231], v[96:111]
	ds_read_b128 v[196:199], v200 offset:4096
	s_waitcnt vmcnt(5)
	ds_write_b128 v179, v[128:131] offset:24576
	s_waitcnt vmcnt(4)
	ds_write_b128 v179, v[136:139] offset:28672
	s_waitcnt lgkmcnt(3)
	v_mfma_f32_32x32x16_bf16 v[80:95], v[232:235], v[208:211], v[80:95]
	v_mfma_f32_32x32x16_bf16 v[64:79], v[232:235], v[228:231], v[64:79]
	ds_read_b128 v[232:235], v200 offset:6144
	s_waitcnt vmcnt(3)
	ds_write_b128 v179, v[144:147] offset:32768
	s_waitcnt vmcnt(2)
	ds_write_b128 v179, v[148:151] offset:36864
	s_waitcnt lgkmcnt(5)
	v_mfma_f32_32x32x16_bf16 v[48:63], v[196:199], v[208:211], v[48:63]
	v_mfma_f32_32x32x16_bf16 v[32:47], v[196:199], v[228:231], v[32:47]
	ds_read_b128 v[196:199], v202
	s_waitcnt vmcnt(1)
	ds_write_b128 v179, v[160:163] offset:40960
	s_waitcnt vmcnt(0)
	ds_write_b128 v179, v[168:171] offset:45056
	s_waitcnt lgkmcnt(5)
	v_mfma_f32_32x32x16_bf16 v[16:31], v[232:235], v[208:211], v[16:31]
	ds_read_b128 v[208:211], v203 offset:16384
	v_mfma_f32_32x32x16_bf16 v[0:15], v[232:235], v[228:231], v[0:15]
	ds_read_b128 v[228:231], v203 offset:18432
	ds_read_b128 v[232:235], v202 offset:2048
	s_waitcnt lgkmcnt(2)
	v_mfma_f32_32x32x16_bf16 v[112:127], v[196:199], v[208:211], v[112:127]
	s_waitcnt lgkmcnt(1)
	v_mfma_f32_32x32x16_bf16 v[96:111], v[196:199], v[228:231], v[96:111]
	ds_read_b128 v[196:199], v202 offset:4096
	s_mov_b32 vcc_lo, 0x1b00000
	v_lshl_add_u64 v[128:129], v[252:253], 0, vcc
	global_load_dwordx4 v[128:131], v[128:129], off offset:192
	s_mov_b32 vcc_lo, 0x1b20000
	v_lshl_add_u64 v[136:137], v[252:253], 0, vcc
	global_load_dwordx4 v[136:139], v[136:137], off offset:192
	s_waitcnt lgkmcnt(1)
	v_mfma_f32_32x32x16_bf16 v[80:95], v[232:235], v[208:211], v[80:95]
	v_mfma_f32_32x32x16_bf16 v[64:79], v[232:235], v[228:231], v[64:79]
	ds_read_b128 v[232:235], v202 offset:6144
	s_mov_b32 vcc_lo, 0x1b40000
	v_lshl_add_u64 v[144:145], v[252:253], 0, vcc
	global_load_dwordx4 v[144:147], v[144:145], off offset:192
	s_mov_b32 vcc_lo, 0x1b60000
	v_lshl_add_u64 v[148:149], v[252:253], 0, vcc
	global_load_dwordx4 v[148:151], v[148:149], off offset:192
	s_waitcnt lgkmcnt(1)
	v_mfma_f32_32x32x16_bf16 v[48:63], v[196:199], v[208:211], v[48:63]
	v_mfma_f32_32x32x16_bf16 v[32:47], v[196:199], v[228:231], v[32:47]
	s_mov_b32 vcc_lo, 0xa00000
	v_lshl_add_u64 v[160:161], v[254:255], 0, vcc
	global_load_dwordx4 v[160:163], v[160:161], off offset:192
	s_mov_b32 vcc_lo, 0xa20000
	v_lshl_add_u64 v[168:169], v[254:255], 0, vcc
	global_load_dwordx4 v[168:171], v[168:169], off offset:192
	s_waitcnt lgkmcnt(0)
	v_mfma_f32_32x32x16_bf16 v[16:31], v[232:235], v[208:211], v[16:31]
	v_mfma_f32_32x32x16_bf16 v[0:15], v[232:235], v[228:231], v[0:15]
	s_waitcnt lgkmcnt(0)
	s_barrier
	ds_read_b128 v[196:199], v200 offset:24576
	ds_read_b128 v[208:211], v201 offset:40960
	ds_read_b128 v[228:231], v201 offset:43008
	ds_read_b128 v[232:235], v200 offset:26624
	s_waitcnt lgkmcnt(2)
	v_mfma_f32_32x32x16_bf16 v[112:127], v[196:199], v[208:211], v[112:127]
	s_waitcnt lgkmcnt(1)
	v_mfma_f32_32x32x16_bf16 v[96:111], v[196:199], v[228:231], v[96:111]
	ds_read_b128 v[196:199], v200 offset:28672
	ds_write_b128 v179, v[132:135]
	ds_write_b128 v179, v[140:143] offset:4096
	s_waitcnt lgkmcnt(3)
	v_mfma_f32_32x32x16_bf16 v[80:95], v[232:235], v[208:211], v[80:95]
	v_mfma_f32_32x32x16_bf16 v[64:79], v[232:235], v[228:231], v[64:79]
	ds_read_b128 v[232:235], v200 offset:30720
	ds_write_b128 v179, v[152:155] offset:8192
	ds_write_b128 v179, v[156:159] offset:12288
	s_waitcnt lgkmcnt(5)
	v_mfma_f32_32x32x16_bf16 v[48:63], v[196:199], v[208:211], v[48:63]
	v_mfma_f32_32x32x16_bf16 v[32:47], v[196:199], v[228:231], v[32:47]
	ds_read_b128 v[196:199], v202 offset:24576
	ds_write_b128 v179, v[164:167] offset:16384
	ds_write_b128 v179, v[172:175] offset:20480
	s_waitcnt lgkmcnt(5)
	v_mfma_f32_32x32x16_bf16 v[16:31], v[232:235], v[208:211], v[16:31]
	ds_read_b128 v[208:211], v203 offset:40960
	v_mfma_f32_32x32x16_bf16 v[0:15], v[232:235], v[228:231], v[0:15]
	ds_read_b128 v[228:231], v203 offset:43008
	ds_read_b128 v[232:235], v202 offset:26624
	s_waitcnt lgkmcnt(2)
	v_mfma_f32_32x32x16_bf16 v[112:127], v[196:199], v[208:211], v[112:127]
	s_waitcnt lgkmcnt(1)
	v_mfma_f32_32x32x16_bf16 v[96:111], v[196:199], v[228:231], v[96:111]
	ds_read_b128 v[196:199], v202 offset:28672
	s_mov_b32 vcc_lo, 0x1b00000
	v_lshl_add_u64 v[132:133], v[252:253], 0, vcc
	global_load_dwordx4 v[132:135], v[132:133], off offset:256
	s_mov_b32 vcc_lo, 0x1b20000
	v_lshl_add_u64 v[140:141], v[252:253], 0, vcc
	global_load_dwordx4 v[140:143], v[140:141], off offset:256
	s_waitcnt lgkmcnt(1)
	v_mfma_f32_32x32x16_bf16 v[80:95], v[232:235], v[208:211], v[80:95]
	v_mfma_f32_32x32x16_bf16 v[64:79], v[232:235], v[228:231], v[64:79]
	ds_read_b128 v[232:235], v202 offset:30720
	s_mov_b32 vcc_lo, 0x1b40000
	v_lshl_add_u64 v[152:153], v[252:253], 0, vcc
	global_load_dwordx4 v[152:155], v[152:153], off offset:256
	s_mov_b32 vcc_lo, 0x1b60000
	v_lshl_add_u64 v[156:157], v[252:253], 0, vcc
	global_load_dwordx4 v[156:159], v[156:157], off offset:256
	s_waitcnt lgkmcnt(1)
	v_mfma_f32_32x32x16_bf16 v[48:63], v[196:199], v[208:211], v[48:63]
	v_mfma_f32_32x32x16_bf16 v[32:47], v[196:199], v[228:231], v[32:47]
	s_mov_b32 vcc_lo, 0xa00000
	v_lshl_add_u64 v[164:165], v[254:255], 0, vcc
	global_load_dwordx4 v[164:167], v[164:165], off offset:256
	s_mov_b32 vcc_lo, 0xa20000
	v_lshl_add_u64 v[172:173], v[254:255], 0, vcc
	global_load_dwordx4 v[172:175], v[172:173], off offset:256
	s_waitcnt lgkmcnt(0)
	v_mfma_f32_32x32x16_bf16 v[16:31], v[232:235], v[208:211], v[16:31]
	v_mfma_f32_32x32x16_bf16 v[0:15], v[232:235], v[228:231], v[0:15]
	v_lshl_add_u64 v[194:195], v[194:195], 0, s[50:51]
	v_lshl_add_u64 v[192:193], v[192:193], 0, s[50:51]
	s_waitcnt lgkmcnt(0)
	s_barrier
	s_branch .LBB0_3203

; template <bool RES, class Epi>
; DEV void gemm_tile_x(const bf16_t* A0, int lda0, const bf16_t* A1, int lda1, int ksplit,
;                      const bf16_t* Bt, int ldb, int K, char* smem, const float* resb, Epi epi) {
;     ...
;   for (int kt = 0; kt < nk; kt += 2) {
;     GEMM_COMPUTE(sbase);
;     if (kt + 1 < nk) gemm_lds_write(g1, sbase + GST + woff, sbase + GST + GSA + woff);
;     if (kt + 3 < nk) gemm_gload(g1, A0, lda0, A1, lda1, ksplit, Bt, ldb, (kt + 3) * 32, tid);
.LBB0_3286:
	s_cmp_lt_i32 s61, 82
	s_cbranch_scc1 .Lfp10_fast
	s_add_i32 s61, s61, 2
	s_cmpk_gt_u32 s61, 0x54
	ds_read_b128 v[194:197], v198
	ds_read_b128 v[206:209], v199 offset:16384
	ds_read_b128 v[210:213], v199 offset:18432
	ds_read_b128 v[216:219], v198 offset:2048
	ds_read_b128 v[252:255], v201 offset:16384
	s_waitcnt lgkmcnt(3)
	v_mfma_f32_32x32x16_bf16 v[112:127], v[194:197], v[206:209], v[112:127]
	s_waitcnt lgkmcnt(2)
	v_mfma_f32_32x32x16_bf16 v[96:111], v[194:197], v[210:213], v[96:111]
	ds_read_b128 v[194:197], v198 offset:4096
	s_waitcnt lgkmcnt(2)
	v_mfma_f32_32x32x16_bf16 v[80:95], v[216:219], v[206:209], v[80:95]
	v_mfma_f32_32x32x16_bf16 v[64:79], v[216:219], v[210:213], v[64:79]
	ds_read_b128 v[216:219], v198 offset:6144
	s_waitcnt lgkmcnt(1)
	v_mfma_f32_32x32x16_bf16 v[48:63], v[194:197], v[206:209], v[48:63]
	v_mfma_f32_32x32x16_bf16 v[32:47], v[194:197], v[210:213], v[32:47]
	ds_read_b128 v[194:197], v200
	s_waitcnt lgkmcnt(1)
	v_mfma_f32_32x32x16_bf16 v[0:15], v[216:219], v[210:213], v[0:15]
	ds_read_b128 v[210:213], v201 offset:18432
	v_mfma_f32_32x32x16_bf16 v[16:31], v[216:219], v[206:209], v[16:31]
	ds_read_b128 v[216:219], v200 offset:2048
	s_waitcnt lgkmcnt(2)
	v_mfma_f32_32x32x16_bf16 v[112:127], v[194:197], v[252:255], v[112:127]
	s_waitcnt lgkmcnt(1)
	v_mfma_f32_32x32x16_bf16 v[96:111], v[194:197], v[210:213], v[96:111]
	ds_read_b128 v[194:197], v200 offset:4096
	s_waitcnt lgkmcnt(1)
	v_mfma_f32_32x32x16_bf16 v[80:95], v[216:219], v[252:255], v[80:95]
	v_mfma_f32_32x32x16_bf16 v[64:79], v[216:219], v[210:213], v[64:79]
	ds_read_b128 v[216:219], v200 offset:6144
	s_waitcnt vmcnt(5)
	ds_write_b128 v179, v[128:131] offset:24576
	s_waitcnt vmcnt(4)
	ds_write_b128 v179, v[136:139] offset:28672
	s_waitcnt vmcnt(3)
	ds_write_b128 v179, v[144:147] offset:32768
	s_waitcnt vmcnt(2)
	ds_write_b128 v179, v[148:151] offset:36864
	s_waitcnt vmcnt(1)
	ds_write_b128 v179, v[160:163] offset:40960
	s_waitcnt vmcnt(0)
	ds_write_b128 v179, v[168:171] offset:45056
	s_waitcnt lgkmcnt(7)
	v_mfma_f32_32x32x16_bf16 v[48:63], v[194:197], v[252:255], v[48:63]
	v_mfma_f32_32x32x16_bf16 v[32:47], v[194:197], v[210:213], v[32:47]
	v_lshl_add_u64 v[196:197], v[192:193], 0, v[180:181]
	v_lshl_add_u64 v[194:195], v[190:191], 0, v[180:181]
	s_waitcnt lgkmcnt(6)
	v_mfma_f32_32x32x16_bf16 v[16:31], v[216:219], v[252:255], v[16:31]
	v_mfma_f32_32x32x16_bf16 v[0:15], v[216:219], v[210:213], v[0:15]
	s_waitcnt lgkmcnt(0)
	s_cbranch_scc1 .LBB0_3288
	v_add_co_u32_e32 v128, vcc, 0x7b00000, v196
	s_nop 1
	v_addc_co_u32_e32 v129, vcc, 0, v197, vcc
	v_add_co_u32_e32 v136, vcc, 0x7b58000, v196
	s_nop 1
	v_addc_co_u32_e32 v137, vcc, 0, v197, vcc
	v_add_co_u32_e32 v144, vcc, 0x7bb0000, v196
	global_load_dwordx4 v[128:131], v[128:129], off offset:192
	s_nop 0
	global_load_dwordx4 v[136:139], v[136:137], off offset:192
	v_addc_co_u32_e32 v145, vcc, 0, v197, vcc
	v_add_co_u32_e32 v148, vcc, 0x7c08000, v196
	s_nop 1
	v_addc_co_u32_e32 v149, vcc, 0, v197, vcc
	v_add_co_u32_e32 v160, vcc, 0x1500000, v194
	global_load_dwordx4 v[144:147], v[144:145], off offset:192
	s_nop 0
	global_load_dwordx4 v[148:151], v[148:149], off offset:192
	v_addc_co_u32_e32 v161, vcc, 0, v195, vcc
	v_add_co_u32_e32 v168, vcc, 0x1558000, v194
	s_nop 1
	v_addc_co_u32_e32 v169, vcc, 0, v195, vcc
	global_load_dwordx4 v[160:163], v[160:161], off offset:192
	s_nop 0
	global_load_dwordx4 v[168:171], v[168:169], off offset:192

; template <bool RES, class Epi>
; DEV void gemm_tile_x(const bf16_t* A0, int lda0, const bf16_t* A1, int lda1, int ksplit,
;                      const bf16_t* Bt, int ldb, int K, char* smem, const float* resb, Epi epi) {
;     ...
;   for (int kt = 0; kt < nk; kt += 2) {
;     GEMM_COMPUTE(sbase);
;     if (kt + 1 < nk) gemm_lds_write(g1, sbase + GST + woff, sbase + GST + GSA + woff);
;     if (kt + 3 < nk) gemm_gload(g1, A0, lda0, A1, lda1, ksplit, Bt, ldb, (kt + 3) * 32, tid);
;     __syncthreads();
;     if (kt + 1 < nk) {
;       GEMM_COMPUTE(sbase + GST);
;       if (kt + 2 < nk) gemm_lds_write(g, sbase + woff, sbase + GSA + woff);
;       if (kt + 4 < nk) gemm_gload(g, A0, lda0, A1, lda1, ksplit, Bt, ldb, (kt + 4) * 32, tid);
;       __syncthreads();
;     }
.Lfp10_fast:
	s_add_i32 s61, s61, 2
	v_lshl_add_u64 v[252:253], v[192:193], 0, v[180:181]
	v_lshl_add_u64 v[254:255], v[190:191], 0, v[180:181]
	s_mov_b32 vcc_hi, 0
	ds_read_b128 v[194:197], v198
	ds_read_b128 v[206:209], v199 offset:16384
	ds_read_b128 v[210:213], v199 offset:18432
	ds_read_b128 v[216:219], v198 offset:2048
	s_waitcnt lgkmcnt(2)
	v_mfma_f32_32x32x16_bf16 v[112:127], v[194:197], v[206:209], v[112:127]
	s_waitcnt lgkmcnt(1)
	v_mfma_f32_32x32x16_bf16 v[96:111], v[194:197], v[210:213], v[96:111]
	ds_read_b128 v[194:197], v198 offset:4096
	s_waitcnt vmcnt(5)
	ds_write_b128 v179, v[128:131] offset:24576
	s_waitcnt vmcnt(4)
	ds_write_b128 v179, v[136:139] offset:28672
	s_waitcnt lgkmcnt(3)
	v_mfma_f32_32x32x16_bf16 v[80:95], v[216:219], v[206:209], v[80:95]
	v_mfma_f32_32x32x16_bf16 v[64:79], v[216:219], v[210:213], v[64:79]
	ds_read_b128 v[216:219], v198 offset:6144
	s_waitcnt vmcnt(3)
	ds_write_b128 v179, v[144:147] offset:32768
	s_waitcnt vmcnt(2)
	ds_write_b128 v179, v[148:151] offset:36864
	s_waitcnt lgkmcnt(5)
	v_mfma_f32_32x32x16_bf16 v[48:63], v[194:197], v[206:209], v[48:63]
	v_mfma_f32_32x32x16_bf16 v[32:47], v[194:197], v[210:213], v[32:47]
	ds_read_b128 v[194:197], v200
	s_waitcnt vmcnt(1)
	ds_write_b128 v179, v[160:163] offset:40960
	s_waitcnt vmcnt(0)
	ds_write_b128 v179, v[168:171] offset:45056
	s_waitcnt lgkmcnt(5)
	v_mfma_f32_32x32x16_bf16 v[16:31], v[216:219], v[206:209], v[16:31]
	ds_read_b128 v[206:209], v201 offset:16384
	v_mfma_f32_32x32x16_bf16 v[0:15], v[216:219], v[210:213], v[0:15]
	ds_read_b128 v[210:213], v201 offset:18432
	ds_read_b128 v[216:219], v200 offset:2048
	s_waitcnt lgkmcnt(2)
	v_mfma_f32_32x32x16_bf16 v[112:127], v[194:197], v[206:209], v[112:127]
	s_waitcnt lgkmcnt(1)
	v_mfma_f32_32x32x16_bf16 v[96:111], v[194:197], v[210:213], v[96:111]
	ds_read_b128 v[194:197], v200 offset:4096
	s_mov_b32 vcc_lo, 0x7b00000
	v_lshl_add_u64 v[128:129], v[252:253], 0, vcc
	global_load_dwordx4 v[128:131], v[128:129], off offset:192
	s_mov_b32 vcc_lo, 0x7b58000
	v_lshl_add_u64 v[136:137], v[252:253], 0, vcc
	global_load_dwordx4 v[136:139], v[136:137], off offset:192
	s_waitcnt lgkmcnt(1)
	v_mfma_f32_32x32x16_bf16 v[80:95], v[216:219], v[206:209], v[80:95]
	v_mfma_f32_32x32x16_bf16 v[64:79], v[216:219], v[210:213], v[64:79]
	ds_read_b128 v[216:219], v200 offset:6144
	s_mov_b32 vcc_lo, 0x7bb0000
	v_lshl_add_u64 v[144:145], v[252:253], 0, vcc
	global_load_dwordx4 v[144:147], v[144:145], off offset:192
	s_mov_b32 vcc_lo, 0x7c08000
	v_lshl_add_u64 v[148:149], v[252:253], 0, vcc
	global_load_dwordx4 v[148:151], v[148:149], off offset:192
	s_waitcnt lgkmcnt(1)
	v_mfma_f32_32x32x16_bf16 v[48:63], v[194:197], v[206:209], v[48:63]
	v_mfma_f32_32x32x16_bf16 v[32:47], v[194:197], v[210:213], v[32:47]
	s_mov_b32 vcc_lo, 0x1500000
	v_lshl_add_u64 v[160:161], v[254:255], 0, vcc
	global_load_dwordx4 v[160:163], v[160:161], off offset:192
	s_mov_b32 vcc_lo, 0x1558000
	v_lshl_add_u64 v[168:169], v[254:255], 0, vcc
	global_load_dwordx4 v[168:171], v[168:169], off offset:192
	s_waitcnt lgkmcnt(0)
	v_mfma_f32_32x32x16_bf16 v[16:31], v[216:219], v[206:209], v[16:31]
	v_mfma_f32_32x32x16_bf16 v[0:15], v[216:219], v[210:213], v[0:15]
	s_waitcnt lgkmcnt(0)
	s_barrier
	ds_read_b128 v[194:197], v198 offset:24576
	ds_read_b128 v[206:209], v199 offset:40960
	ds_read_b128 v[210:213], v199 offset:43008
	ds_read_b128 v[216:219], v198 offset:26624
	s_waitcnt lgkmcnt(2)
	v_mfma_f32_32x32x16_bf16 v[112:127], v[194:197], v[206:209], v[112:127]
	s_waitcnt lgkmcnt(1)
	v_mfma_f32_32x32x16_bf16 v[96:111], v[194:197], v[210:213], v[96:111]
	ds_read_b128 v[194:197], v198 offset:28672
	ds_write_b128 v179, v[132:135]
	ds_write_b128 v179, v[140:143] offset:4096
	s_waitcnt lgkmcnt(3)
	v_mfma_f32_32x32x16_bf16 v[80:95], v[216:219], v[206:209], v[80:95]
	v_mfma_f32_32x32x16_bf16 v[64:79], v[216:219], v[210:213], v[64:79]
	ds_read_b128 v[216:219], v198 offset:30720
	ds_write_b128 v179, v[152:155] offset:8192
	ds_write_b128 v179, v[156:159] offset:12288
	s_waitcnt lgkmcnt(5)
	v_mfma_f32_32x32x16_bf16 v[48:63], v[194:197], v[206:209], v[48:63]
	v_mfma_f32_32x32x16_bf16 v[32:47], v[194:197], v[210:213], v[32:47]
	ds_read_b128 v[194:197], v200 offset:24576
	ds_write_b128 v179, v[164:167] offset:16384
	ds_write_b128 v179, v[172:175] offset:20480
	s_waitcnt lgkmcnt(5)
	v_mfma_f32_32x32x16_bf16 v[16:31], v[216:219], v[206:209], v[16:31]
	ds_read_b128 v[206:209], v201 offset:40960
	v_mfma_f32_32x32x16_bf16 v[0:15], v[216:219], v[210:213], v[0:15]
	ds_read_b128 v[210:213], v201 offset:43008
	ds_read_b128 v[216:219], v200 offset:26624
	s_waitcnt lgkmcnt(2)
	v_mfma_f32_32x32x16_bf16 v[112:127], v[194:197], v[206:209], v[112:127]
	s_waitcnt lgkmcnt(1)
	v_mfma_f32_32x32x16_bf16 v[96:111], v[194:197], v[210:213], v[96:111]
	ds_read_b128 v[194:197], v200 offset:28672
	s_mov_b32 vcc_lo, 0x7b00000
	v_lshl_add_u64 v[132:133], v[252:253], 0, vcc
	global_load_dwordx4 v[132:135], v[132:133], off offset:256
	s_mov_b32 vcc_lo, 0x7b58000
	v_lshl_add_u64 v[140:141], v[252:253], 0, vcc
	global_load_dwordx4 v[140:143], v[140:141], off offset:256
	s_waitcnt lgkmcnt(1)
	v_mfma_f32_32x32x16_bf16 v[80:95], v[216:219], v[206:209], v[80:95]
	v_mfma_f32_32x32x16_bf16 v[64:79], v[216:219], v[210:213], v[64:79]
	ds_read_b128 v[216:219], v200 offset:30720
	s_mov_b32 vcc_lo, 0x7bb0000
	v_lshl_add_u64 v[152:153], v[252:253], 0, vcc
	global_load_dwordx4 v[152:155], v[152:153], off offset:256
	s_mov_b32 vcc_lo, 0x7c08000
	v_lshl_add_u64 v[156:157], v[252:253], 0, vcc
	global_load_dwordx4 v[156:159], v[156:157], off offset:256
	s_waitcnt lgkmcnt(1)
	v_mfma_f32_32x32x16_bf16 v[48:63], v[194:197], v[206:209], v[48:63]
	v_mfma_f32_32x32x16_bf16 v[32:47], v[194:197], v[210:213], v[32:47]
	s_mov_b32 vcc_lo, 0x1500000
	v_lshl_add_u64 v[164:165], v[254:255], 0, vcc
	global_load_dwordx4 v[164:167], v[164:165], off offset:256
	s_mov_b32 vcc_lo, 0x1558000
	v_lshl_add_u64 v[172:173], v[254:255], 0, vcc
	global_load_dwordx4 v[172:175], v[172:173], off offset:256
	s_waitcnt lgkmcnt(0)
	v_mfma_f32_32x32x16_bf16 v[16:31], v[216:219], v[206:209], v[16:31]
	v_mfma_f32_32x32x16_bf16 v[0:15], v[216:219], v[210:213], v[0:15]
	v_lshl_add_u64 v[190:191], v[190:191], 0, s[50:51]
	v_lshl_add_u64 v[192:193], v[192:193], 0, s[50:51]
	s_waitcnt lgkmcnt(0)
	s_barrier
	s_branch .LBB0_3286
